# same segment-head cleanup in the P4 and P5 K-loops (setprio before the barrier, satisfied lgkmcnt(0) removed, no-op flip pairs removed, also in the half-unit loop)
# baseline (speedup 1.0000x reference)
.Lhu_k1_ym:
	s_setprio 1
	v_mfma_f32_16x16x32_bf16 v[102:105], v[150:153], v[166:169], v[102:105]
	v_mfma_f32_16x16x32_bf16 v[70:73], v[158:161], v[166:169], v[70:73]
	v_mfma_f32_16x16x32_bf16 v[114:117], v[150:153], v[174:177], v[114:117]
	v_mfma_f32_16x16x32_bf16 v[82:85], v[158:161], v[174:177], v[82:85]
	v_mfma_f32_16x16x32_bf16 v[110:113], v[150:153], v[182:185], v[110:113]
	v_mfma_f32_16x16x32_bf16 v[78:81], v[158:161], v[182:185], v[78:81]
	v_mfma_f32_16x16x32_bf16 v[106:109], v[150:153], v[190:193], v[106:109]
	v_mfma_f32_16x16x32_bf16 v[74:77], v[158:161], v[190:193], v[74:77]
	v_mfma_f32_16x16x32_bf16 v[102:105], v[154:157], v[170:173], v[102:105]
	v_mfma_f32_16x16x32_bf16 v[70:73], v[162:165], v[170:173], v[70:73]
	v_mfma_f32_16x16x32_bf16 v[114:117], v[154:157], v[178:181], v[114:117]
	v_mfma_f32_16x16x32_bf16 v[82:85], v[162:165], v[178:181], v[82:85]
	v_mfma_f32_16x16x32_bf16 v[110:113], v[154:157], v[186:189], v[110:113]
	v_mfma_f32_16x16x32_bf16 v[78:81], v[162:165], v[186:189], v[78:81]
	v_mfma_f32_16x16x32_bf16 v[106:109], v[154:157], v[194:197], v[106:109]
	v_mfma_f32_16x16x32_bf16 v[74:77], v[162:165], v[194:197], v[74:77]
	v_mfma_f32_16x16x32_bf16 v[130:133], v[134:137], v[166:169], v[130:133]
	v_mfma_f32_16x16x32_bf16 v[98:101], v[142:145], v[166:169], v[98:101]
	v_mfma_f32_16x16x32_bf16 v[126:129], v[134:137], v[174:177], v[126:129]
	v_mfma_f32_16x16x32_bf16 v[94:97], v[142:145], v[174:177], v[94:97]
	v_mfma_f32_16x16x32_bf16 v[122:125], v[134:137], v[182:185], v[122:125]
	v_mfma_f32_16x16x32_bf16 v[90:93], v[142:145], v[182:185], v[90:93]
	v_mfma_f32_16x16x32_bf16 v[118:121], v[134:137], v[190:193], v[118:121]
	v_mfma_f32_16x16x32_bf16 v[86:89], v[142:145], v[190:193], v[86:89]
	v_mfma_f32_16x16x32_bf16 v[130:133], v[138:141], v[170:173], v[130:133]
	v_mfma_f32_16x16x32_bf16 v[98:101], v[146:149], v[170:173], v[98:101]
	v_mfma_f32_16x16x32_bf16 v[126:129], v[138:141], v[178:181], v[126:129]
	v_mfma_f32_16x16x32_bf16 v[94:97], v[146:149], v[178:181], v[94:97]
	v_mfma_f32_16x16x32_bf16 v[122:125], v[138:141], v[186:189], v[122:125]
	v_mfma_f32_16x16x32_bf16 v[90:93], v[146:149], v[186:189], v[90:93]
	v_mfma_f32_16x16x32_bf16 v[118:121], v[138:141], v[194:197], v[118:121]
	v_mfma_f32_16x16x32_bf16 v[86:89], v[146:149], v[194:197], v[86:89]
	s_setprio 0
	s_branch .Lhu_k1_cb
.Lhu_k1_x:
	s_setprio 1
	v_mfma_f32_16x16x32_bf16 v[102:105], v[150:153], v[166:169], v[102:105]
	v_mfma_f32_16x16x32_bf16 v[70:73], v[158:161], v[166:169], v[70:73]
	v_mfma_f32_16x16x32_bf16 v[114:117], v[150:153], v[174:177], v[114:117]
	v_mfma_f32_16x16x32_bf16 v[82:85], v[158:161], v[174:177], v[82:85]
	v_mfma_f32_16x16x32_bf16 v[110:113], v[150:153], v[182:185], v[110:113]
	v_mfma_f32_16x16x32_bf16 v[78:81], v[158:161], v[182:185], v[78:81]
	v_mfma_f32_16x16x32_bf16 v[106:109], v[150:153], v[190:193], v[106:109]
	v_mfma_f32_16x16x32_bf16 v[74:77], v[158:161], v[190:193], v[74:77]
	v_mfma_f32_16x16x32_bf16 v[102:105], v[154:157], v[170:173], v[102:105]
	v_mfma_f32_16x16x32_bf16 v[70:73], v[162:165], v[170:173], v[70:73]
	v_mfma_f32_16x16x32_bf16 v[114:117], v[154:157], v[178:181], v[114:117]
	v_mfma_f32_16x16x32_bf16 v[82:85], v[162:165], v[178:181], v[82:85]
	v_mfma_f32_16x16x32_bf16 v[110:113], v[154:157], v[186:189], v[110:113]
	v_mfma_f32_16x16x32_bf16 v[78:81], v[162:165], v[186:189], v[78:81]
	v_mfma_f32_16x16x32_bf16 v[106:109], v[154:157], v[194:197], v[106:109]
	v_mfma_f32_16x16x32_bf16 v[74:77], v[162:165], v[194:197], v[74:77]
	v_mfma_f32_16x16x32_bf16 v[130:133], v[134:137], v[166:169], v[130:133]
	v_mfma_f32_16x16x32_bf16 v[98:101], v[142:145], v[166:169], v[98:101]
	v_mfma_f32_16x16x32_bf16 v[126:129], v[134:137], v[174:177], v[126:129]
	v_mfma_f32_16x16x32_bf16 v[94:97], v[142:145], v[174:177], v[94:97]
	v_mfma_f32_16x16x32_bf16 v[122:125], v[134:137], v[182:185], v[122:125]
	v_mfma_f32_16x16x32_bf16 v[90:93], v[142:145], v[182:185], v[90:93]
	v_mfma_f32_16x16x32_bf16 v[118:121], v[134:137], v[190:193], v[118:121]
	v_mfma_f32_16x16x32_bf16 v[86:89], v[142:145], v[190:193], v[86:89]
	v_mfma_f32_16x16x32_bf16 v[130:133], v[138:141], v[170:173], v[130:133]
	v_mfma_f32_16x16x32_bf16 v[98:101], v[146:149], v[170:173], v[98:101]
	v_mfma_f32_16x16x32_bf16 v[126:129], v[138:141], v[178:181], v[126:129]
	v_mfma_f32_16x16x32_bf16 v[94:97], v[146:149], v[178:181], v[94:97]
	v_mfma_f32_16x16x32_bf16 v[122:125], v[138:141], v[186:189], v[122:125]
	v_mfma_f32_16x16x32_bf16 v[90:93], v[146:149], v[186:189], v[90:93]
	v_mfma_f32_16x16x32_bf16 v[118:121], v[138:141], v[194:197], v[118:121]
	v_mfma_f32_16x16x32_bf16 v[86:89], v[146:149], v[194:197], v[86:89]
	s_setprio 0
	s_waitcnt vmcnt(6)

.Lhu_k3_x:
	s_setprio 1
	v_mfma_f32_16x16x32_bf16 v[102:105], v[150:153], v[166:169], v[102:105]
	v_mfma_f32_16x16x32_bf16 v[70:73], v[158:161], v[166:169], v[70:73]
	v_mfma_f32_16x16x32_bf16 v[114:117], v[150:153], v[174:177], v[114:117]
	v_mfma_f32_16x16x32_bf16 v[82:85], v[158:161], v[174:177], v[82:85]
	v_mfma_f32_16x16x32_bf16 v[110:113], v[150:153], v[182:185], v[110:113]
	v_mfma_f32_16x16x32_bf16 v[78:81], v[158:161], v[182:185], v[78:81]
	v_mfma_f32_16x16x32_bf16 v[106:109], v[150:153], v[190:193], v[106:109]
	v_mfma_f32_16x16x32_bf16 v[74:77], v[158:161], v[190:193], v[74:77]
	v_mfma_f32_16x16x32_bf16 v[102:105], v[154:157], v[170:173], v[102:105]
	v_mfma_f32_16x16x32_bf16 v[70:73], v[162:165], v[170:173], v[70:73]
	v_mfma_f32_16x16x32_bf16 v[114:117], v[154:157], v[178:181], v[114:117]
	v_mfma_f32_16x16x32_bf16 v[82:85], v[162:165], v[178:181], v[82:85]
	v_mfma_f32_16x16x32_bf16 v[110:113], v[154:157], v[186:189], v[110:113]
	v_mfma_f32_16x16x32_bf16 v[78:81], v[162:165], v[186:189], v[78:81]
	v_mfma_f32_16x16x32_bf16 v[106:109], v[154:157], v[194:197], v[106:109]
	v_mfma_f32_16x16x32_bf16 v[74:77], v[162:165], v[194:197], v[74:77]
	v_mfma_f32_16x16x32_bf16 v[130:133], v[134:137], v[166:169], v[130:133]
	v_mfma_f32_16x16x32_bf16 v[98:101], v[142:145], v[166:169], v[98:101]
	v_mfma_f32_16x16x32_bf16 v[126:129], v[134:137], v[174:177], v[126:129]
	v_mfma_f32_16x16x32_bf16 v[94:97], v[142:145], v[174:177], v[94:97]
	v_mfma_f32_16x16x32_bf16 v[122:125], v[134:137], v[182:185], v[122:125]
	v_mfma_f32_16x16x32_bf16 v[90:93], v[142:145], v[182:185], v[90:93]
	v_mfma_f32_16x16x32_bf16 v[118:121], v[134:137], v[190:193], v[118:121]
	v_mfma_f32_16x16x32_bf16 v[86:89], v[142:145], v[190:193], v[86:89]
	v_mfma_f32_16x16x32_bf16 v[130:133], v[138:141], v[170:173], v[130:133]
	v_mfma_f32_16x16x32_bf16 v[98:101], v[146:149], v[170:173], v[98:101]
	v_mfma_f32_16x16x32_bf16 v[126:129], v[138:141], v[178:181], v[126:129]
	v_mfma_f32_16x16x32_bf16 v[94:97], v[146:149], v[178:181], v[94:97]
	v_mfma_f32_16x16x32_bf16 v[122:125], v[138:141], v[186:189], v[122:125]
	v_mfma_f32_16x16x32_bf16 v[90:93], v[146:149], v[186:189], v[90:93]
	v_mfma_f32_16x16x32_bf16 v[118:121], v[138:141], v[194:197], v[118:121]
	v_mfma_f32_16x16x32_bf16 v[86:89], v[146:149], v[194:197], v[86:89]
	s_setprio 0
	s_cmp_eq_u32 s45, 12
	s_cbranch_scc1 .Lhu_k3_x0
	s_waitcnt vmcnt(6)
	s_branch .Lhu_k3_cb

.Lhu_k4_x:
	s_setprio 1
	v_mfma_f32_16x16x32_bf16 v[102:105], v[150:153], v[166:169], v[102:105]
	v_mfma_f32_16x16x32_bf16 v[70:73], v[158:161], v[166:169], v[70:73]
	v_mfma_f32_16x16x32_bf16 v[114:117], v[150:153], v[174:177], v[114:117]
	v_mfma_f32_16x16x32_bf16 v[82:85], v[158:161], v[174:177], v[82:85]
	v_mfma_f32_16x16x32_bf16 v[110:113], v[150:153], v[182:185], v[110:113]
	v_mfma_f32_16x16x32_bf16 v[78:81], v[158:161], v[182:185], v[78:81]
	v_mfma_f32_16x16x32_bf16 v[106:109], v[150:153], v[190:193], v[106:109]
	v_mfma_f32_16x16x32_bf16 v[74:77], v[158:161], v[190:193], v[74:77]
	v_mfma_f32_16x16x32_bf16 v[102:105], v[154:157], v[170:173], v[102:105]
	v_mfma_f32_16x16x32_bf16 v[70:73], v[162:165], v[170:173], v[70:73]
	v_mfma_f32_16x16x32_bf16 v[114:117], v[154:157], v[178:181], v[114:117]
	v_mfma_f32_16x16x32_bf16 v[82:85], v[162:165], v[178:181], v[82:85]
	v_mfma_f32_16x16x32_bf16 v[110:113], v[154:157], v[186:189], v[110:113]
	v_mfma_f32_16x16x32_bf16 v[78:81], v[162:165], v[186:189], v[78:81]
	v_mfma_f32_16x16x32_bf16 v[106:109], v[154:157], v[194:197], v[106:109]
	v_mfma_f32_16x16x32_bf16 v[74:77], v[162:165], v[194:197], v[74:77]
	v_mfma_f32_16x16x32_bf16 v[130:133], v[134:137], v[166:169], v[130:133]
	v_mfma_f32_16x16x32_bf16 v[98:101], v[142:145], v[166:169], v[98:101]
	v_mfma_f32_16x16x32_bf16 v[126:129], v[134:137], v[174:177], v[126:129]
	v_mfma_f32_16x16x32_bf16 v[94:97], v[142:145], v[174:177], v[94:97]
	v_mfma_f32_16x16x32_bf16 v[122:125], v[134:137], v[182:185], v[122:125]
	v_mfma_f32_16x16x32_bf16 v[90:93], v[142:145], v[182:185], v[90:93]
	v_mfma_f32_16x16x32_bf16 v[118:121], v[134:137], v[190:193], v[118:121]
	v_mfma_f32_16x16x32_bf16 v[86:89], v[142:145], v[190:193], v[86:89]
	v_mfma_f32_16x16x32_bf16 v[130:133], v[138:141], v[170:173], v[130:133]
	v_mfma_f32_16x16x32_bf16 v[98:101], v[146:149], v[170:173], v[98:101]
	v_mfma_f32_16x16x32_bf16 v[126:129], v[138:141], v[178:181], v[126:129]
	v_mfma_f32_16x16x32_bf16 v[94:97], v[146:149], v[178:181], v[94:97]
	v_mfma_f32_16x16x32_bf16 v[122:125], v[138:141], v[186:189], v[122:125]
	v_mfma_f32_16x16x32_bf16 v[90:93], v[146:149], v[186:189], v[90:93]
	v_mfma_f32_16x16x32_bf16 v[118:121], v[138:141], v[194:197], v[118:121]
	v_mfma_f32_16x16x32_bf16 v[86:89], v[146:149], v[194:197], v[86:89]
	s_setprio 0
	s_waitcnt vmcnt(0)

.LBB0_534:
	s_waitcnt lgkmcnt(0)
	s_setprio 1
	s_barrier
	v_mfma_f32_16x16x32_bf16 v[66:69], v[150:153], v[190:193], v[66:69]
	v_mfma_f32_16x16x32_bf16 v[62:65], v[158:161], v[190:193], v[62:65]
	v_mfma_f32_16x16x32_bf16 v[58:61], v[150:153], v[182:185], v[58:61]
	v_mfma_f32_16x16x32_bf16 v[54:57], v[158:161], v[182:185], v[54:57]
	v_mfma_f32_16x16x32_bf16 v[50:53], v[150:153], v[174:177], v[50:53]
	v_mfma_f32_16x16x32_bf16 v[46:49], v[158:161], v[174:177], v[46:49]
	v_mfma_f32_16x16x32_bf16 v[42:45], v[150:153], v[166:169], v[42:45]
	v_mfma_f32_16x16x32_bf16 v[38:41], v[158:161], v[166:169], v[38:41]
	v_mfma_f32_16x16x32_bf16 v[66:69], v[154:157], v[194:197], v[66:69]
	v_mfma_f32_16x16x32_bf16 v[62:65], v[162:165], v[194:197], v[62:65]
	v_mfma_f32_16x16x32_bf16 v[58:61], v[154:157], v[186:189], v[58:61]
	v_mfma_f32_16x16x32_bf16 v[54:57], v[162:165], v[186:189], v[54:57]
	v_mfma_f32_16x16x32_bf16 v[50:53], v[154:157], v[178:181], v[50:53]
	v_mfma_f32_16x16x32_bf16 v[46:49], v[162:165], v[178:181], v[46:49]
	v_mfma_f32_16x16x32_bf16 v[42:45], v[154:157], v[170:173], v[42:45]
	v_mfma_f32_16x16x32_bf16 v[38:41], v[162:165], v[170:173], v[38:41]
	v_mfma_f32_16x16x32_bf16 v[34:37], v[134:137], v[190:193], v[34:37]
	v_mfma_f32_16x16x32_bf16 v[30:33], v[142:145], v[190:193], v[30:33]
	v_mfma_f32_16x16x32_bf16 v[26:29], v[134:137], v[182:185], v[26:29]
	v_mfma_f32_16x16x32_bf16 v[22:25], v[142:145], v[182:185], v[22:25]
	v_mfma_f32_16x16x32_bf16 v[18:21], v[134:137], v[174:177], v[18:21]
	v_mfma_f32_16x16x32_bf16 v[14:17], v[142:145], v[174:177], v[14:17]
	v_mfma_f32_16x16x32_bf16 v[8:11], v[134:137], v[166:169], v[10:13]
	v_mfma_f32_16x16x32_bf16 v[4:7], v[142:145], v[166:169], v[4:7]
	v_mfma_f32_16x16x32_bf16 v[34:37], v[138:141], v[194:197], v[34:37]
	v_mfma_f32_16x16x32_bf16 v[30:33], v[146:149], v[194:197], v[30:33]
	v_mfma_f32_16x16x32_bf16 v[26:29], v[138:141], v[186:189], v[26:29]
	v_mfma_f32_16x16x32_bf16 v[22:25], v[146:149], v[186:189], v[22:25]
	v_mfma_f32_16x16x32_bf16 v[18:21], v[138:141], v[178:181], v[18:21]
	v_mfma_f32_16x16x32_bf16 v[14:17], v[146:149], v[178:181], v[14:17]
	v_mfma_f32_16x16x32_bf16 v[10:13], v[138:141], v[170:173], v[8:11]
	v_mfma_f32_16x16x32_bf16 v[6:9], v[146:149], v[170:173], v[4:7]
	s_setprio 0
	s_barrier
	s_add_i32 s59, s59, 2
	s_add_u32 s31, s31, 0x100
	s_addc_u32 s35, s35, 0
	s_cmp_gt_u32 s59, 13
	s_cbranch_scc1 .LBB0_547
.LBB0_535:
	v_add_u32_e32 v3, 0x10000, v248
	ds_read_b128 v[150:153], v3
	ds_read_b128 v[154:157], v3 offset:1024
	ds_read_b128 v[158:161], v3 offset:2048
	ds_read_b128 v[162:165], v3 offset:3072
	v_add_u32_e32 v3, 0x14000, v248
	s_mov_b64 s[8:9], s[44:45]
	ds_read_b128 v[134:137], v3
	ds_read_b128 v[138:141], v3 offset:1024
	ds_read_b128 v[142:145], v3 offset:2048
	ds_read_b128 v[146:149], v3 offset:3072
	s_add_u32 s44, s8, 0x100
	s_addc_u32 s45, s9, 0
	s_cmp_eq_u32 s59, 12
	s_cselect_b64 s[48:49], -1, 0
	s_and_b64 s[2:3], s[48:49], exec
	s_cselect_b32 s3, s39, s35
	s_cselect_b32 s2, s38, s31
	s_cselect_b32 s47, s37, s45
	s_cselect_b32 s46, s36, s44
	v_lshl_add_u64 v[4:5], s[8:9], 0, v[214:215]
	s_add_i32 m0, s55, 0xc000
	ds_read_b128 v[166:169], v249
	ds_read_b128 v[170:173], v249 offset:1024
	ds_read_b128 v[174:177], v249 offset:2048
	ds_read_b128 v[178:181], v249 offset:3072
	ds_read_b128 v[182:185], v249 offset:4096
	ds_read_b128 v[186:189], v249 offset:5120
	ds_read_b128 v[190:193], v249 offset:6144
	ds_read_b128 v[194:197], v249 offset:7168
	global_load_lds_dwordx4 v[4:5], off
	v_lshl_add_u64 v[4:5], s[8:9], 0, v[216:217]
	s_add_i32 m0, s55, 0xe000
	s_nop 0
	global_load_lds_dwordx4 v[4:5], off
	s_waitcnt vmcnt(8)
	s_waitcnt lgkmcnt(0)
	s_setprio 1
	s_barrier
	v_mfma_f32_16x16x32_bf16 v[130:133], v[150:153], v[166:169], v[130:133]
	v_mfma_f32_16x16x32_bf16 v[126:129], v[158:161], v[166:169], v[126:129]
	v_mfma_f32_16x16x32_bf16 v[122:125], v[150:153], v[174:177], v[122:125]
	v_mfma_f32_16x16x32_bf16 v[118:121], v[158:161], v[174:177], v[118:121]
	v_mfma_f32_16x16x32_bf16 v[114:117], v[150:153], v[182:185], v[114:117]
	v_mfma_f32_16x16x32_bf16 v[110:113], v[158:161], v[182:185], v[110:113]
	v_mfma_f32_16x16x32_bf16 v[106:109], v[150:153], v[190:193], v[106:109]
	v_mfma_f32_16x16x32_bf16 v[102:105], v[158:161], v[190:193], v[102:105]
	v_mfma_f32_16x16x32_bf16 v[130:133], v[154:157], v[170:173], v[130:133]
	v_mfma_f32_16x16x32_bf16 v[126:129], v[162:165], v[170:173], v[126:129]
	v_mfma_f32_16x16x32_bf16 v[122:125], v[154:157], v[178:181], v[122:125]
	v_mfma_f32_16x16x32_bf16 v[118:121], v[162:165], v[178:181], v[118:121]
	v_mfma_f32_16x16x32_bf16 v[114:117], v[154:157], v[186:189], v[114:117]
	v_mfma_f32_16x16x32_bf16 v[110:113], v[162:165], v[186:189], v[110:113]
	v_mfma_f32_16x16x32_bf16 v[106:109], v[154:157], v[194:197], v[106:109]
	v_mfma_f32_16x16x32_bf16 v[102:105], v[162:165], v[194:197], v[102:105]
	v_mfma_f32_16x16x32_bf16 v[98:101], v[134:137], v[166:169], v[98:101]
	v_mfma_f32_16x16x32_bf16 v[94:97], v[142:145], v[166:169], v[94:97]
	v_mfma_f32_16x16x32_bf16 v[90:93], v[134:137], v[174:177], v[90:93]
	v_mfma_f32_16x16x32_bf16 v[86:89], v[142:145], v[174:177], v[86:89]
	v_mfma_f32_16x16x32_bf16 v[82:85], v[134:137], v[182:185], v[82:85]
	v_mfma_f32_16x16x32_bf16 v[78:81], v[142:145], v[182:185], v[78:81]
	v_mfma_f32_16x16x32_bf16 v[74:77], v[134:137], v[190:193], v[74:77]
	v_mfma_f32_16x16x32_bf16 v[70:73], v[142:145], v[190:193], v[70:73]
	v_mfma_f32_16x16x32_bf16 v[98:101], v[138:141], v[170:173], v[98:101]
	v_mfma_f32_16x16x32_bf16 v[94:97], v[146:149], v[170:173], v[94:97]
	v_mfma_f32_16x16x32_bf16 v[90:93], v[138:141], v[178:181], v[90:93]
	v_mfma_f32_16x16x32_bf16 v[86:89], v[146:149], v[178:181], v[86:89]
	v_mfma_f32_16x16x32_bf16 v[82:85], v[138:141], v[186:189], v[82:85]
	v_mfma_f32_16x16x32_bf16 v[78:81], v[146:149], v[186:189], v[78:81]
	v_mfma_f32_16x16x32_bf16 v[74:77], v[138:141], v[194:197], v[74:77]
	v_mfma_f32_16x16x32_bf16 v[70:73], v[146:149], v[194:197], v[70:73]
	s_setprio 0
	s_barrier
	ds_read_b128 v[190:193], v249 offset:16384
	ds_read_b128 v[194:197], v249 offset:17408
	ds_read_b128 v[182:185], v249 offset:18432
	ds_read_b128 v[186:189], v249 offset:19456
	ds_read_b128 v[174:177], v249 offset:20480
	ds_read_b128 v[178:181], v249 offset:21504
	ds_read_b128 v[166:169], v249 offset:22528
	ds_read_b128 v[170:173], v249 offset:23552
	s_and_b64 s[8:9], s[6:7], s[48:49]
	s_mov_b64 s[48:49], -1
	s_and_b64 vcc, exec, s[8:9]
	v_lshl_add_u64 v[228:229], s[2:3], 0, v[204:205]
	v_lshl_add_u64 v[226:227], s[2:3], 0, v[210:211]
	v_lshl_add_u64 v[224:225], s[46:47], 0, v[202:203]
	v_lshl_add_u64 v[222:223], s[46:47], 0, v[208:209]
	s_cbranch_vccnz .LBB0_537
	s_add_i32 m0, s55, 0x10000
	s_nop 0
	global_load_lds_dwordx4 v[228:229], off
	s_add_i32 m0, s55, 0x12000
	s_add_u32 s48, s2, 0x80000
	s_addc_u32 s49, s3, 0
	global_load_lds_dwordx4 v[226:227], off
	v_lshl_add_u64 v[4:5], s[48:49], 0, v[204:205]
	s_add_i32 m0, s55, 0x14000
	s_nop 0
	global_load_lds_dwordx4 v[4:5], off
	v_lshl_add_u64 v[4:5], s[48:49], 0, v[210:211]
	s_add_i32 m0, s55, 0x16000
	s_mov_b64 s[48:49], 0
	global_load_lds_dwordx4 v[4:5], off
	s_mov_b32 m0, s55
	s_nop 0
	global_load_lds_dwordx4 v[224:225], off
	s_add_i32 m0, s55, 0x2000
	s_nop 0
	global_load_lds_dwordx4 v[222:223], off
	s_waitcnt vmcnt(8)

.LBB0_539:
	s_waitcnt lgkmcnt(0)
	s_xor_b64 s[48:49], s[8:9], -1
	s_setprio 1
	s_barrier
	v_mfma_f32_16x16x32_bf16 v[66:69], v[150:153], v[190:193], v[66:69]
	v_mfma_f32_16x16x32_bf16 v[62:65], v[158:161], v[190:193], v[62:65]
	v_mfma_f32_16x16x32_bf16 v[58:61], v[150:153], v[182:185], v[58:61]
	v_mfma_f32_16x16x32_bf16 v[54:57], v[158:161], v[182:185], v[54:57]
	v_mfma_f32_16x16x32_bf16 v[50:53], v[150:153], v[174:177], v[50:53]
	v_mfma_f32_16x16x32_bf16 v[46:49], v[158:161], v[174:177], v[46:49]
	v_mfma_f32_16x16x32_bf16 v[42:45], v[150:153], v[166:169], v[42:45]
	v_mfma_f32_16x16x32_bf16 v[38:41], v[158:161], v[166:169], v[38:41]
	v_mfma_f32_16x16x32_bf16 v[66:69], v[154:157], v[194:197], v[66:69]
	v_mfma_f32_16x16x32_bf16 v[62:65], v[162:165], v[194:197], v[62:65]
	v_mfma_f32_16x16x32_bf16 v[58:61], v[154:157], v[186:189], v[58:61]
	v_mfma_f32_16x16x32_bf16 v[54:57], v[162:165], v[186:189], v[54:57]
	v_mfma_f32_16x16x32_bf16 v[50:53], v[154:157], v[178:181], v[50:53]
	v_mfma_f32_16x16x32_bf16 v[46:49], v[162:165], v[178:181], v[46:49]
	v_mfma_f32_16x16x32_bf16 v[42:45], v[154:157], v[170:173], v[42:45]
	v_mfma_f32_16x16x32_bf16 v[38:41], v[162:165], v[170:173], v[38:41]
	v_mfma_f32_16x16x32_bf16 v[34:37], v[134:137], v[190:193], v[34:37]
	v_mfma_f32_16x16x32_bf16 v[30:33], v[142:145], v[190:193], v[30:33]
	v_mfma_f32_16x16x32_bf16 v[26:29], v[134:137], v[182:185], v[26:29]
	v_mfma_f32_16x16x32_bf16 v[22:25], v[142:145], v[182:185], v[22:25]
	v_mfma_f32_16x16x32_bf16 v[18:21], v[134:137], v[174:177], v[18:21]
	v_mfma_f32_16x16x32_bf16 v[14:17], v[142:145], v[174:177], v[14:17]
	v_mfma_f32_16x16x32_bf16 v[10:13], v[134:137], v[166:169], v[10:13]
	v_mfma_f32_16x16x32_bf16 v[4:7], v[142:145], v[166:169], v[6:9]
	v_mfma_f32_16x16x32_bf16 v[34:37], v[138:141], v[194:197], v[34:37]
	v_mfma_f32_16x16x32_bf16 v[30:33], v[146:149], v[194:197], v[30:33]
	v_mfma_f32_16x16x32_bf16 v[26:29], v[138:141], v[186:189], v[26:29]
	v_mfma_f32_16x16x32_bf16 v[22:25], v[146:149], v[186:189], v[22:25]
	v_mfma_f32_16x16x32_bf16 v[18:21], v[138:141], v[178:181], v[18:21]
	v_mfma_f32_16x16x32_bf16 v[14:17], v[146:149], v[178:181], v[14:17]
	v_mfma_f32_16x16x32_bf16 v[10:13], v[138:141], v[170:173], v[10:13]
	v_mfma_f32_16x16x32_bf16 v[4:7], v[146:149], v[170:173], v[4:7]
	s_setprio 0
	s_barrier
	v_add_u32_e32 v3, 0x18000, v248
	ds_read_b128 v[150:153], v3
	ds_read_b128 v[154:157], v3 offset:1024
	ds_read_b128 v[158:161], v3 offset:2048
	ds_read_b128 v[162:165], v3 offset:3072
	v_add_u32_e32 v3, 0x1c000, v248
	ds_read_b128 v[134:137], v3
	ds_read_b128 v[138:141], v3 offset:1024
	ds_read_b128 v[142:145], v3 offset:2048
	ds_read_b128 v[146:149], v3 offset:3072
	ds_read_b128 v[190:193], v249 offset:32768
	ds_read_b128 v[194:197], v249 offset:33792
	ds_read_b128 v[182:185], v249 offset:34816
	ds_read_b128 v[186:189], v249 offset:35840
	ds_read_b128 v[174:177], v249 offset:36864
	ds_read_b128 v[178:181], v249 offset:37888
	ds_read_b128 v[166:169], v249 offset:38912
	ds_read_b128 v[170:173], v249 offset:39936
	v_cndmask_b32_e64 v3, 0, 1, s[48:49]
	v_cmp_ne_u32_e64 s[8:9], 1, v3
	s_andn2_b64 vcc, exec, s[48:49]
	s_mov_b64 s[48:49], -1
	s_cbranch_vccnz .LBB0_541
	s_add_u32 s46, s46, 0x80000
	s_addc_u32 s47, s47, 0
	v_lshl_add_u64 v[8:9], s[46:47], 0, v[202:203]
	s_add_i32 m0, s55, 0x4000
	s_mov_b64 s[48:49], 0
	global_load_lds_dwordx4 v[8:9], off
	v_lshl_add_u64 v[8:9], s[46:47], 0, v[208:209]
	s_add_i32 m0, s55, 0x6000
	s_nop 0
	global_load_lds_dwordx4 v[8:9], off
	s_waitcnt vmcnt(8)

.LBB0_543:
	s_waitcnt lgkmcnt(0)
	s_setprio 1
	s_barrier
	v_mfma_f32_16x16x32_bf16 v[130:133], v[150:153], v[190:193], v[130:133]
	v_mfma_f32_16x16x32_bf16 v[126:129], v[158:161], v[190:193], v[126:129]
	v_mfma_f32_16x16x32_bf16 v[122:125], v[150:153], v[182:185], v[122:125]
	v_mfma_f32_16x16x32_bf16 v[118:121], v[158:161], v[182:185], v[118:121]
	v_mfma_f32_16x16x32_bf16 v[114:117], v[150:153], v[174:177], v[114:117]
	v_mfma_f32_16x16x32_bf16 v[110:113], v[158:161], v[174:177], v[110:113]
	v_mfma_f32_16x16x32_bf16 v[106:109], v[150:153], v[166:169], v[106:109]
	v_mfma_f32_16x16x32_bf16 v[102:105], v[158:161], v[166:169], v[102:105]
	v_mfma_f32_16x16x32_bf16 v[130:133], v[154:157], v[194:197], v[130:133]
	v_mfma_f32_16x16x32_bf16 v[126:129], v[162:165], v[194:197], v[126:129]
	v_mfma_f32_16x16x32_bf16 v[122:125], v[154:157], v[186:189], v[122:125]
	v_mfma_f32_16x16x32_bf16 v[118:121], v[162:165], v[186:189], v[118:121]
	v_mfma_f32_16x16x32_bf16 v[114:117], v[154:157], v[178:181], v[114:117]
	v_mfma_f32_16x16x32_bf16 v[110:113], v[162:165], v[178:181], v[110:113]
	v_mfma_f32_16x16x32_bf16 v[106:109], v[154:157], v[170:173], v[106:109]
	v_mfma_f32_16x16x32_bf16 v[102:105], v[162:165], v[170:173], v[102:105]
	v_mfma_f32_16x16x32_bf16 v[98:101], v[134:137], v[190:193], v[98:101]
	v_mfma_f32_16x16x32_bf16 v[94:97], v[142:145], v[190:193], v[94:97]
	v_mfma_f32_16x16x32_bf16 v[90:93], v[134:137], v[182:185], v[90:93]
	v_mfma_f32_16x16x32_bf16 v[86:89], v[142:145], v[182:185], v[86:89]
	v_mfma_f32_16x16x32_bf16 v[82:85], v[134:137], v[174:177], v[82:85]
	v_mfma_f32_16x16x32_bf16 v[78:81], v[142:145], v[174:177], v[78:81]
	v_mfma_f32_16x16x32_bf16 v[74:77], v[134:137], v[166:169], v[74:77]
	v_mfma_f32_16x16x32_bf16 v[70:73], v[142:145], v[166:169], v[70:73]
	v_mfma_f32_16x16x32_bf16 v[98:101], v[138:141], v[194:197], v[98:101]
	v_mfma_f32_16x16x32_bf16 v[94:97], v[146:149], v[194:197], v[94:97]
	v_mfma_f32_16x16x32_bf16 v[90:93], v[138:141], v[186:189], v[90:93]
	v_mfma_f32_16x16x32_bf16 v[86:89], v[146:149], v[186:189], v[86:89]
	v_mfma_f32_16x16x32_bf16 v[82:85], v[138:141], v[178:181], v[82:85]
	v_mfma_f32_16x16x32_bf16 v[78:81], v[146:149], v[178:181], v[78:81]
	v_mfma_f32_16x16x32_bf16 v[74:77], v[138:141], v[170:173], v[74:77]
	v_mfma_f32_16x16x32_bf16 v[70:73], v[146:149], v[170:173], v[70:73]
	s_setprio 0
	s_barrier
	ds_read_b128 v[190:193], v249 offset:49152
	ds_read_b128 v[194:197], v249 offset:50176
	ds_read_b128 v[182:185], v249 offset:51200
	ds_read_b128 v[186:189], v249 offset:52224
	ds_read_b128 v[174:177], v249 offset:53248
	ds_read_b128 v[178:181], v249 offset:54272
	ds_read_b128 v[166:169], v249 offset:55296
	ds_read_b128 v[170:173], v249 offset:56320
	s_and_b64 vcc, exec, s[8:9]
	s_mov_b64 s[8:9], -1
	s_cbranch_vccnz .LBB0_545
	v_lshl_add_u64 v[8:9], v[228:229], 0, s[18:19]
	s_add_i32 m0, s55, 0x18000
	s_mov_b64 s[8:9], 0
	global_load_lds_dwordx4 v[8:9], off
	s_add_i32 m0, s55, 0x1a000
	s_add_u32 s2, s2, 0x80080
	v_lshl_add_u64 v[8:9], v[226:227], 0, s[18:19]
	s_addc_u32 s3, s3, 0
	global_load_lds_dwordx4 v[8:9], off
	v_lshl_add_u64 v[8:9], s[2:3], 0, v[204:205]
	s_add_i32 m0, s55, 0x1c000
	s_nop 0
	global_load_lds_dwordx4 v[8:9], off
	v_lshl_add_u64 v[8:9], s[2:3], 0, v[210:211]
	s_add_i32 m0, s55, 0x1e000
	s_nop 0
	global_load_lds_dwordx4 v[8:9], off
	v_lshl_add_u64 v[8:9], v[224:225], 0, s[18:19]
	s_add_i32 m0, s55, 0x8000
	s_nop 0
	global_load_lds_dwordx4 v[8:9], off
	v_lshl_add_u64 v[8:9], v[222:223], 0, s[18:19]
	s_add_i32 m0, s55, 0xa000
	s_nop 0
	global_load_lds_dwordx4 v[8:9], off
	s_waitcnt vmcnt(8)

.LBB0_635:
	s_waitcnt lgkmcnt(0)
	s_setprio 1
	s_barrier
	v_mfma_f32_16x16x32_bf16 v[78:81], v[146:149], v[186:189], v[78:81]
	v_mfma_f32_16x16x32_bf16 v[74:77], v[154:157], v[186:189], v[74:77]
	v_mfma_f32_16x16x32_bf16 v[50:53], v[146:149], v[178:181], v[50:53]
	v_mfma_f32_16x16x32_bf16 v[42:45], v[154:157], v[178:181], v[42:45]
	v_mfma_f32_16x16x32_bf16 v[34:37], v[146:149], v[170:173], v[34:37]
	v_mfma_f32_16x16x32_bf16 v[26:29], v[154:157], v[170:173], v[26:29]
	v_mfma_f32_16x16x32_bf16 v[18:21], v[146:149], v[162:165], v[18:21]
	v_mfma_f32_16x16x32_bf16 v[10:13], v[154:157], v[162:165], v[10:13]
	v_mfma_f32_16x16x32_bf16 v[78:81], v[150:153], v[190:193], v[78:81]
	v_mfma_f32_16x16x32_bf16 v[74:77], v[158:161], v[190:193], v[74:77]
	v_mfma_f32_16x16x32_bf16 v[50:53], v[150:153], v[182:185], v[50:53]
	v_mfma_f32_16x16x32_bf16 v[42:45], v[158:161], v[182:185], v[42:45]
	v_mfma_f32_16x16x32_bf16 v[34:37], v[150:153], v[174:177], v[34:37]
	v_mfma_f32_16x16x32_bf16 v[26:29], v[158:161], v[174:177], v[26:29]
	v_mfma_f32_16x16x32_bf16 v[18:21], v[150:153], v[166:169], v[18:21]
	v_mfma_f32_16x16x32_bf16 v[10:13], v[158:161], v[166:169], v[10:13]
	v_mfma_f32_16x16x32_bf16 v[54:57], v[130:133], v[186:189], v[54:57]
	v_mfma_f32_16x16x32_bf16 v[46:49], v[138:141], v[186:189], v[46:49]
	v_mfma_f32_16x16x32_bf16 v[38:41], v[130:133], v[178:181], v[38:41]
	v_mfma_f32_16x16x32_bf16 v[30:33], v[138:141], v[178:181], v[30:33]
	v_mfma_f32_16x16x32_bf16 v[22:25], v[130:133], v[170:173], v[22:25]
	v_mfma_f32_16x16x32_bf16 v[14:17], v[138:141], v[170:173], v[14:17]
	v_mfma_f32_16x16x32_bf16 v[6:9], v[130:133], v[162:165], v[6:9]
	v_mfma_f32_16x16x32_bf16 v[2:5], v[138:141], v[162:165], v[2:5]
	v_mfma_f32_16x16x32_bf16 v[54:57], v[134:137], v[190:193], v[54:57]
	v_mfma_f32_16x16x32_bf16 v[46:49], v[142:145], v[190:193], v[46:49]
	v_mfma_f32_16x16x32_bf16 v[38:41], v[134:137], v[182:185], v[38:41]
	v_mfma_f32_16x16x32_bf16 v[30:33], v[142:145], v[182:185], v[30:33]
	v_mfma_f32_16x16x32_bf16 v[22:25], v[134:137], v[174:177], v[22:25]
	v_mfma_f32_16x16x32_bf16 v[14:17], v[142:145], v[174:177], v[14:17]
	v_mfma_f32_16x16x32_bf16 v[6:9], v[134:137], v[166:169], v[6:9]
	v_mfma_f32_16x16x32_bf16 v[2:5], v[142:145], v[166:169], v[2:5]
	s_setprio 0
	s_barrier
	s_add_i32 s54, s54, 2
	s_add_u32 s2, s2, 0x100
	s_addc_u32 s3, s3, 0
	s_cmp_gt_u32 s54, 13
	s_cbranch_scc1 .LBB0_648
.LBB0_636:
	s_add_u32 s4, s14, s2
	s_addc_u32 s5, s15, s3
	s_add_u32 s28, s4, 0x100
	v_add_u32_e32 v130, 0x10000, v222
	v_add_u32_e32 v142, 0x14000, v222
	s_addc_u32 s29, s5, 0
	ds_read_b128 v[146:149], v130
	ds_read_b128 v[150:153], v130 offset:1024
	ds_read_b128 v[154:157], v130 offset:2048
	ds_read_b128 v[158:161], v130 offset:3072
	ds_read_b128 v[130:133], v142
	ds_read_b128 v[134:137], v142 offset:1024
	ds_read_b128 v[138:141], v142 offset:2048
	ds_read_b128 v[142:145], v142 offset:3072
	s_add_u32 s30, s50, s2
	s_addc_u32 s31, s51, s3
	s_cmpk_eq_i32 s2, 0x700
	s_cselect_b64 s[4:5], -1, 0
	s_and_b64 s[26:27], s[4:5], exec
	s_cselect_b32 s27, s19, s31
	s_cselect_b32 s26, s53, s30
	s_cselect_b32 s29, s21, s29
	s_cselect_b32 s28, s52, s28
	v_lshl_add_u64 v[212:213], v[208:209], 0, s[2:3]
	s_add_i32 m0, s13, 0xc000
	ds_read_b128 v[162:165], v223
	ds_read_b128 v[166:169], v223 offset:1024
	ds_read_b128 v[170:173], v223 offset:2048
	ds_read_b128 v[174:177], v223 offset:3072
	ds_read_b128 v[178:181], v223 offset:4096
	ds_read_b128 v[182:185], v223 offset:5120
	ds_read_b128 v[186:189], v223 offset:6144
	ds_read_b128 v[190:193], v223 offset:7168
	global_load_lds_dwordx4 v[212:213], off
	v_lshl_add_u64 v[212:213], v[210:211], 0, s[2:3]
	s_add_i32 m0, s13, 0xe000
	s_nop 0
	global_load_lds_dwordx4 v[212:213], off
	s_waitcnt vmcnt(8)
	s_waitcnt lgkmcnt(0)
	s_setprio 1
	s_barrier
	v_mfma_f32_16x16x32_bf16 v[126:129], v[146:149], v[162:165], v[126:129]
	v_mfma_f32_16x16x32_bf16 v[122:125], v[154:157], v[162:165], v[122:125]
	v_mfma_f32_16x16x32_bf16 v[118:121], v[146:149], v[170:173], v[118:121]
	v_mfma_f32_16x16x32_bf16 v[106:109], v[154:157], v[170:173], v[106:109]
	v_mfma_f32_16x16x32_bf16 v[94:97], v[146:149], v[178:181], v[94:97]
	v_mfma_f32_16x16x32_bf16 v[82:85], v[154:157], v[178:181], v[82:85]
	v_mfma_f32_16x16x32_bf16 v[62:65], v[146:149], v[186:189], v[62:65]
	v_mfma_f32_16x16x32_bf16 v[66:69], v[154:157], v[186:189], v[66:69]
	v_mfma_f32_16x16x32_bf16 v[126:129], v[150:153], v[166:169], v[126:129]
	v_mfma_f32_16x16x32_bf16 v[122:125], v[158:161], v[166:169], v[122:125]
	v_mfma_f32_16x16x32_bf16 v[118:121], v[150:153], v[174:177], v[118:121]
	v_mfma_f32_16x16x32_bf16 v[106:109], v[158:161], v[174:177], v[106:109]
	v_mfma_f32_16x16x32_bf16 v[94:97], v[150:153], v[182:185], v[94:97]
	v_mfma_f32_16x16x32_bf16 v[82:85], v[158:161], v[182:185], v[82:85]
	v_mfma_f32_16x16x32_bf16 v[62:65], v[150:153], v[190:193], v[62:65]
	v_mfma_f32_16x16x32_bf16 v[66:69], v[158:161], v[190:193], v[66:69]
	v_mfma_f32_16x16x32_bf16 v[114:117], v[130:133], v[162:165], v[114:117]
	v_mfma_f32_16x16x32_bf16 v[110:113], v[138:141], v[162:165], v[110:113]
	v_mfma_f32_16x16x32_bf16 v[102:105], v[130:133], v[170:173], v[102:105]
	v_mfma_f32_16x16x32_bf16 v[90:93], v[138:141], v[170:173], v[90:93]
	v_mfma_f32_16x16x32_bf16 v[70:73], v[130:133], v[178:181], v[70:73]
	v_mfma_f32_16x16x32_bf16 v[58:61], v[138:141], v[178:181], v[58:61]
	v_mfma_f32_16x16x32_bf16 v[98:101], v[130:133], v[186:189], v[98:101]
	v_mfma_f32_16x16x32_bf16 v[86:89], v[138:141], v[186:189], v[86:89]
	v_mfma_f32_16x16x32_bf16 v[114:117], v[134:137], v[166:169], v[114:117]
	v_mfma_f32_16x16x32_bf16 v[110:113], v[142:145], v[166:169], v[110:113]
	v_mfma_f32_16x16x32_bf16 v[102:105], v[134:137], v[174:177], v[102:105]
	v_mfma_f32_16x16x32_bf16 v[90:93], v[142:145], v[174:177], v[90:93]
	v_mfma_f32_16x16x32_bf16 v[70:73], v[134:137], v[182:185], v[70:73]
	v_mfma_f32_16x16x32_bf16 v[58:61], v[142:145], v[182:185], v[58:61]
	v_mfma_f32_16x16x32_bf16 v[98:101], v[134:137], v[190:193], v[98:101]
	v_mfma_f32_16x16x32_bf16 v[86:89], v[142:145], v[190:193], v[86:89]
	s_setprio 0
	s_barrier
	ds_read_b128 v[186:189], v223 offset:16384
	ds_read_b128 v[190:193], v223 offset:17408
	ds_read_b128 v[178:181], v223 offset:18432
	ds_read_b128 v[182:185], v223 offset:19456
	ds_read_b128 v[170:173], v223 offset:20480
	ds_read_b128 v[174:177], v223 offset:21504
	ds_read_b128 v[162:165], v223 offset:22528
	ds_read_b128 v[166:169], v223 offset:23552
	s_and_b64 s[4:5], s[0:1], s[4:5]
	s_mov_b64 s[30:31], -1
	s_and_b64 vcc, exec, s[4:5]
	v_lshl_add_u64 v[218:219], s[26:27], 0, v[194:195]
	v_lshl_add_u64 v[216:217], s[26:27], 0, v[196:197]
	v_lshl_add_u64 v[214:215], s[28:29], 0, v[194:195]
	v_lshl_add_u64 v[212:213], s[28:29], 0, v[196:197]
	s_cbranch_vccnz .LBB0_638
	s_add_i32 m0, s13, 0x10000
	s_nop 0
	global_load_lds_dwordx4 v[218:219], off
	s_add_i32 m0, s13, 0x12000
	s_add_u32 s30, s26, 0x40000
	s_addc_u32 s31, s27, 0
	global_load_lds_dwordx4 v[216:217], off
	v_lshl_add_u64 v[224:225], s[30:31], 0, v[194:195]
	s_add_i32 m0, s13, 0x14000
	s_nop 0
	global_load_lds_dwordx4 v[224:225], off
	v_lshl_add_u64 v[224:225], s[30:31], 0, v[196:197]
	s_add_i32 m0, s13, 0x16000
	s_mov_b64 s[30:31], 0
	global_load_lds_dwordx4 v[224:225], off
	s_mov_b32 m0, s13
	s_nop 0
	global_load_lds_dwordx4 v[214:215], off
	s_mov_b32 m0, s39
	s_nop 0
	global_load_lds_dwordx4 v[212:213], off
	s_waitcnt vmcnt(8)

.LBB0_640:
	s_waitcnt lgkmcnt(0)
	s_xor_b64 s[30:31], s[4:5], -1
	s_setprio 1
	s_barrier
	v_mfma_f32_16x16x32_bf16 v[78:81], v[146:149], v[186:189], v[78:81]
	v_mfma_f32_16x16x32_bf16 v[74:77], v[154:157], v[186:189], v[74:77]
	v_mfma_f32_16x16x32_bf16 v[50:53], v[146:149], v[178:181], v[50:53]
	v_mfma_f32_16x16x32_bf16 v[42:45], v[154:157], v[178:181], v[42:45]
	v_mfma_f32_16x16x32_bf16 v[34:37], v[146:149], v[170:173], v[34:37]
	v_mfma_f32_16x16x32_bf16 v[26:29], v[154:157], v[170:173], v[26:29]
	v_mfma_f32_16x16x32_bf16 v[18:21], v[146:149], v[162:165], v[18:21]
	v_mfma_f32_16x16x32_bf16 v[10:13], v[154:157], v[162:165], v[10:13]
	v_mfma_f32_16x16x32_bf16 v[78:81], v[150:153], v[190:193], v[78:81]
	v_mfma_f32_16x16x32_bf16 v[74:77], v[158:161], v[190:193], v[74:77]
	v_mfma_f32_16x16x32_bf16 v[50:53], v[150:153], v[182:185], v[50:53]
	v_mfma_f32_16x16x32_bf16 v[42:45], v[158:161], v[182:185], v[42:45]
	v_mfma_f32_16x16x32_bf16 v[34:37], v[150:153], v[174:177], v[34:37]
	v_mfma_f32_16x16x32_bf16 v[26:29], v[158:161], v[174:177], v[26:29]
	v_mfma_f32_16x16x32_bf16 v[18:21], v[150:153], v[166:169], v[18:21]
	v_mfma_f32_16x16x32_bf16 v[10:13], v[158:161], v[166:169], v[10:13]
	v_mfma_f32_16x16x32_bf16 v[54:57], v[130:133], v[186:189], v[54:57]
	v_mfma_f32_16x16x32_bf16 v[46:49], v[138:141], v[186:189], v[46:49]
	v_mfma_f32_16x16x32_bf16 v[38:41], v[130:133], v[178:181], v[38:41]
	v_mfma_f32_16x16x32_bf16 v[30:33], v[138:141], v[178:181], v[30:33]
	v_mfma_f32_16x16x32_bf16 v[22:25], v[130:133], v[170:173], v[22:25]
	v_mfma_f32_16x16x32_bf16 v[14:17], v[138:141], v[170:173], v[14:17]
	v_mfma_f32_16x16x32_bf16 v[6:9], v[130:133], v[162:165], v[6:9]
	v_mfma_f32_16x16x32_bf16 v[2:5], v[138:141], v[162:165], v[2:5]
	v_mfma_f32_16x16x32_bf16 v[54:57], v[134:137], v[190:193], v[54:57]
	v_mfma_f32_16x16x32_bf16 v[46:49], v[142:145], v[190:193], v[46:49]
	v_mfma_f32_16x16x32_bf16 v[38:41], v[134:137], v[182:185], v[38:41]
	v_mfma_f32_16x16x32_bf16 v[30:33], v[142:145], v[182:185], v[30:33]
	v_mfma_f32_16x16x32_bf16 v[22:25], v[134:137], v[174:177], v[22:25]
	v_mfma_f32_16x16x32_bf16 v[14:17], v[142:145], v[174:177], v[14:17]
	v_mfma_f32_16x16x32_bf16 v[6:9], v[134:137], v[166:169], v[6:9]
	v_mfma_f32_16x16x32_bf16 v[2:5], v[142:145], v[166:169], v[2:5]
	s_setprio 0
	s_barrier
	v_add_u32_e32 v130, 0x18000, v222
	v_add_u32_e32 v142, 0x1c000, v222
	ds_read_b128 v[146:149], v130
	ds_read_b128 v[150:153], v130 offset:1024
	ds_read_b128 v[154:157], v130 offset:2048
	ds_read_b128 v[158:161], v130 offset:3072
	ds_read_b128 v[130:133], v142
	ds_read_b128 v[134:137], v142 offset:1024
	ds_read_b128 v[138:141], v142 offset:2048
	ds_read_b128 v[142:145], v142 offset:3072
	ds_read_b128 v[186:189], v223 offset:32768
	ds_read_b128 v[190:193], v223 offset:33792
	ds_read_b128 v[178:181], v223 offset:34816
	ds_read_b128 v[182:185], v223 offset:35840
	ds_read_b128 v[170:173], v223 offset:36864
	ds_read_b128 v[174:177], v223 offset:37888
	ds_read_b128 v[162:165], v223 offset:38912
	ds_read_b128 v[166:169], v223 offset:39936
	v_cndmask_b32_e64 v224, 0, 1, s[30:31]
	v_cmp_ne_u32_e64 s[4:5], 1, v224
	s_andn2_b64 vcc, exec, s[30:31]
	s_mov_b64 s[30:31], -1
	s_cbranch_vccnz .LBB0_642
	s_add_u32 s28, s28, 0x40000
	s_addc_u32 s29, s29, 0
	s_mov_b32 m0, s40
	v_lshl_add_u64 v[224:225], s[28:29], 0, v[194:195]
	global_load_lds_dwordx4 v[224:225], off
	v_lshl_add_u64 v[224:225], s[28:29], 0, v[196:197]
	s_mov_b32 m0, s41
	s_mov_b64 s[30:31], 0
	global_load_lds_dwordx4 v[224:225], off
	s_waitcnt vmcnt(8)

.LBB0_644:
	s_waitcnt lgkmcnt(0)
	s_setprio 1
	s_barrier
	v_mfma_f32_16x16x32_bf16 v[126:129], v[146:149], v[186:189], v[126:129]
	v_mfma_f32_16x16x32_bf16 v[122:125], v[154:157], v[186:189], v[122:125]
	v_mfma_f32_16x16x32_bf16 v[118:121], v[146:149], v[178:181], v[118:121]
	v_mfma_f32_16x16x32_bf16 v[106:109], v[154:157], v[178:181], v[106:109]
	v_mfma_f32_16x16x32_bf16 v[94:97], v[146:149], v[170:173], v[94:97]
	v_mfma_f32_16x16x32_bf16 v[82:85], v[154:157], v[170:173], v[82:85]
	v_mfma_f32_16x16x32_bf16 v[62:65], v[146:149], v[162:165], v[62:65]
	v_mfma_f32_16x16x32_bf16 v[66:69], v[154:157], v[162:165], v[66:69]
	v_mfma_f32_16x16x32_bf16 v[126:129], v[150:153], v[190:193], v[126:129]
	v_mfma_f32_16x16x32_bf16 v[122:125], v[158:161], v[190:193], v[122:125]
	v_mfma_f32_16x16x32_bf16 v[118:121], v[150:153], v[182:185], v[118:121]
	v_mfma_f32_16x16x32_bf16 v[106:109], v[158:161], v[182:185], v[106:109]
	v_mfma_f32_16x16x32_bf16 v[94:97], v[150:153], v[174:177], v[94:97]
	v_mfma_f32_16x16x32_bf16 v[82:85], v[158:161], v[174:177], v[82:85]
	v_mfma_f32_16x16x32_bf16 v[62:65], v[150:153], v[166:169], v[62:65]
	v_mfma_f32_16x16x32_bf16 v[66:69], v[158:161], v[166:169], v[66:69]
	v_mfma_f32_16x16x32_bf16 v[114:117], v[130:133], v[186:189], v[114:117]
	v_mfma_f32_16x16x32_bf16 v[110:113], v[138:141], v[186:189], v[110:113]
	v_mfma_f32_16x16x32_bf16 v[102:105], v[130:133], v[178:181], v[102:105]
	v_mfma_f32_16x16x32_bf16 v[90:93], v[138:141], v[178:181], v[90:93]
	v_mfma_f32_16x16x32_bf16 v[70:73], v[130:133], v[170:173], v[70:73]
	v_mfma_f32_16x16x32_bf16 v[58:61], v[138:141], v[170:173], v[58:61]
	v_mfma_f32_16x16x32_bf16 v[98:101], v[130:133], v[162:165], v[98:101]
	v_mfma_f32_16x16x32_bf16 v[86:89], v[138:141], v[162:165], v[86:89]
	v_mfma_f32_16x16x32_bf16 v[114:117], v[134:137], v[190:193], v[114:117]
	v_mfma_f32_16x16x32_bf16 v[110:113], v[142:145], v[190:193], v[110:113]
	v_mfma_f32_16x16x32_bf16 v[102:105], v[134:137], v[182:185], v[102:105]
	v_mfma_f32_16x16x32_bf16 v[90:93], v[142:145], v[182:185], v[90:93]
	v_mfma_f32_16x16x32_bf16 v[70:73], v[134:137], v[174:177], v[70:73]
	v_mfma_f32_16x16x32_bf16 v[58:61], v[142:145], v[174:177], v[58:61]
	v_mfma_f32_16x16x32_bf16 v[98:101], v[134:137], v[166:169], v[98:101]
	v_mfma_f32_16x16x32_bf16 v[86:89], v[142:145], v[166:169], v[86:89]
	s_setprio 0
	s_barrier
	ds_read_b128 v[186:189], v223 offset:49152
	ds_read_b128 v[190:193], v223 offset:50176
	ds_read_b128 v[178:181], v223 offset:51200
	ds_read_b128 v[182:185], v223 offset:52224
	ds_read_b128 v[170:173], v223 offset:53248
	ds_read_b128 v[174:177], v223 offset:54272
	ds_read_b128 v[162:165], v223 offset:55296
	ds_read_b128 v[166:169], v223 offset:56320
	s_and_b64 vcc, exec, s[4:5]
	s_mov_b64 s[4:5], -1
	s_cbranch_vccnz .LBB0_646
	s_mov_b32 m0, s43
	v_lshl_add_u64 v[218:219], v[218:219], 0, s[16:17]
	s_add_u32 s4, s26, 0x40080
	global_load_lds_dwordx4 v[218:219], off
	v_lshl_add_u64 v[216:217], v[216:217], 0, s[16:17]
	s_mov_b32 m0, s44
	s_addc_u32 s5, s27, 0
	global_load_lds_dwordx4 v[216:217], off
	v_lshl_add_u64 v[216:217], s[4:5], 0, v[194:195]
	s_mov_b32 m0, s47
	v_lshl_add_u64 v[214:215], v[214:215], 0, s[16:17]
	global_load_lds_dwordx4 v[216:217], off
	v_lshl_add_u64 v[216:217], s[4:5], 0, v[196:197]
	s_mov_b32 m0, s48
	v_lshl_add_u64 v[212:213], v[212:213], 0, s[16:17]
	global_load_lds_dwordx4 v[216:217], off
	s_mov_b32 m0, s45
	s_mov_b64 s[4:5], 0
	global_load_lds_dwordx4 v[214:215], off
	s_mov_b32 m0, s46
	s_nop 0
	global_load_lds_dwordx4 v[212:213], off
	s_waitcnt vmcnt(8)
